# attention loop: map-1 K fragment address VALU moved into the shadow of the deferred MFMAs
# baseline (speedup 1.0000x reference)
; #define MFMA32(a, b, c) __builtin_amdgcn_mfma_f32_32x32x16_bf16((a), (b), (c), 0, 0, 0)
; #define WAIT_BAR0() asm volatile("s_waitcnt vmcnt(0) lgkmcnt(0)\n\ts_barrier" ::: "memory")
; #define DMA_TILE(kt_, so_) do { glds16(kgp + (size_t)(kt_) * 64 * 128, dk0 + (so_)); glds16(kgp + (size_t)(kt_) * 64 * 128 + 32 * 128, dk0 + (so_) + 8192); \
;     glds16(vgp + (kt_) * 64, dk0 + (so_) + 16384); glds16(vgp + (size_t)64 * SEQ + (kt_) * 64, dk0 + (so_) + 24576); } while (0)
; DI void attn_item(const Params& p, char* lds, int l, int bh, int jt, float lam, float outscale) {
;     ...
;   for (int kt = 0; kt < nkt; ++kt) {
;     WAIT_BAR0();
;     const unsigned so = (kt & 1) * 32768;
;     if (kt + 1 < nkt) DMA_TILE(kt + 1, 32768 - so);
;     if (kt <= my_last) {
;     ...
;       bf16x8 pa0[2], pa1[2];
;       f32x16 S0, S1;
; #pragma unroll
;       for (int e = 0; e < 16; ++e) { S0[e] = 0.f; S1[e] = 0.f; }
; #pragma unroll
;       for (int ks = 0; ks < 4; ++ks) {
;         S0 = MFMA32(KFRAG(0, 0, ks), QFRAG(0, ks), S0);
;         S1 = MFMA32(KFRAG(0, 1, ks), QFRAG(1, ks), S1);
;       }
;     ...
;       for (int s = 0; s < 2; ++s) {
; #pragma unroll
;         for (int d = 0; d < 4; ++d) {
;           const bf16x8 vf = VFRAG(1, d, s);
;           O0[d] = MFMA32(vf, pc0[s], O0[d]);
;           O1[d] = MFMA32(vf, pc1[s], O1[d]);
;         }
.LBB0_727:
	s_cmp_gt_i32 s35, s25
	s_cbranch_scc1 .Lattn_a_idle
	v_add_u32_e32 v203, s49, v252
	ds_read_b128 v[226:229], v251 offset:32768
	ds_read_b128 v[160:163], v203
	v_xor_b32_e32 v204, 0x20, v203
	ds_read_b128 v[230:233], v251 offset:40960
	ds_read_b128 v[164:167], v204
	v_xor_b32_e32 v205, 0x40, v203
	ds_read_b128 v[240:243], v251 offset:49152
	ds_read_b128 v[168:171], v205
	v_xor_b32_e32 v209, 0x60, v203
	ds_read_b128 v[192:195], v251 offset:57344
	ds_read_b128 v[172:175], v209
	s_cmp_eq_u32 s35, 0
	s_cbranch_scc1 .Lattn_nodefer
	v_mfma_f32_32x32x16_bf16 v[96:111], v[210:213], v[180:183], v[96:111]
	v_mfma_f32_32x32x16_bf16 v[80:95], v[214:217], v[180:183], v[80:95]
	v_mfma_f32_32x32x16_bf16 v[48:63], v[218:221], v[180:183], v[48:63]
	v_mfma_f32_32x32x16_bf16 v[16:31], v[222:225], v[180:183], v[16:31]
.Lattn_nodefer:
	v_xor_b32_e32 v235, 0x80, v203
	v_xor_b32_e32 v236, 0xa0, v203
	v_xor_b32_e32 v237, 0xc0, v203
	v_xor_b32_e32 v244, 0xe0, v203
	s_waitcnt lgkmcnt(6)
	v_mfma_f32_32x32x16_bf16 v[144:159], v[160:163], v[226:229], 0
	ds_read_b128 v[210:213], v251
	ds_read_b128 v[160:163], v235
	s_cmp_ge_i32 s27, s24
	s_cbranch_scc1 .Ldma_skip_1
	s_mov_b32 m0, s54
	s_nop 0
	global_load_lds_dwordx4 v208, s[50:51]
